# S5 chunk recurrence as a blocked scan across the 8 waves (was 128 serial steps on wave 0), on top of fragment-order Win/MW and group-major U layouts
# speedup vs baseline: 1.0046x; 1.0007x over previous
; #define LAS __attribute__((address_space(3)))
; __device__ __forceinline__ unsigned cvt_pk_bf16(float lo, float hi) { unsigned r; asm("v_cvt_pk_bf16_f32 %0, %1, %2" : "=v"(r) : "v"(lo), "v"(hi)); return r; }
; #define LDS_WAIT() asm volatile("s_waitcnt lgkmcnt(0)" ::: "memory")
; __device__ __forceinline__ void s5_prompt(const Args& a, LAS unsigned char* lds, int b, int g, int tid, int lane, int wave) {
;     ...
;     bf16x8 am[24];
;     { const int mt = wave; const bf16_t* mw = MW + (size_t)(32 * mt + r32) * 384 + 8 * hh;
; #pragma unroll
;       for (int ks = 0; ks < 16; ++ks) if (ks < 2 * mt + 2) am[ks] = *(const bf16x8*)(mw + 16 * ks);
; #pragma unroll
;       for (int kq = 0; kq < 8; ++kq) am[16 + kq] = *(const bf16x8*)(mw + 256 + 16 * kq); }
;     if (wave == 0) {
;         const LAS float* zp = (const LAS float*)ZS + lane;
;         LAS unsigned short* sp = (LAS unsigned short*)ZS + lane;
;         float sr = 0.f, si = 0.f;
; #pragma unroll 1
;         for (int jb = 0; jb < 16; ++jb) {
;             asm volatile("" : "+v"(zp), "+v"(sp));
;             float zr[8], zi[8];
; #pragma unroll
;             for (int i = 0; i < 8; ++i) { zr[i] = zp[i * (S5_PITCH / 4)]; zi[i] = zp[i * (S5_PITCH / 4) + 64]; }
;             LDS_WAIT();
; #pragma unroll
;             for (int i = 0; i < 8; ++i) {
;                 const unsigned w = cvt_pk_bf16(sr, si);
;                 sp[i * (S5_PITCH / 2)] = (unsigned short)(w & 0xffffu);
;                 sp[i * (S5_PITCH / 2) + 64] = (unsigned short)(w >> 16);
;                 const float nr = l16r * sr - l16i * si + zr[i], ni = l16r * si + l16i * sr + zi[i];
;                 sr = nr; si = ni;
;             }
;             zp += 8 * (S5_PITCH / 4); sp += 8 * (S5_PITCH / 2);
;         }
;         a.out[O_PS5RE + (size_t)(b * NG + g) * NP + lane] = sr;
;         a.out[O_PS5IM + (size_t)(b * NG + g) * NP + lane] = si;
;     }
.LBB0_587:
	global_load_dwordx4 v[130:133], v229, s[48:49]
	global_load_dwordx4 v[134:137], v229, s[48:49] offset:1024
	global_load_dwordx4 v[138:141], v229, s[48:49] offset:2048
	global_load_dwordx4 v[142:145], v229, s[48:49] offset:3072
	global_load_dwordx4 v[146:149], v230, s[48:49]
	global_load_dwordx4 v[150:153], v230, s[48:49] offset:1024
	global_load_dwordx4 v[154:157], v230, s[48:49] offset:2048
	global_load_dwordx4 v[158:161], v230, s[48:49] offset:3072
	v_cndmask_b32_e64 v2, 0, 1, s[18:19]
	v_cmp_ne_u32_e64 s[0:1], 1, v2
	v_readlane_b32 s38, v254, 12
	s_lshr_b32 s38, s38, 6
	s_mul_i32 s39, s38, 0x2100
	v_mov_b32_e32 v26, v36
	v_mov_b32_e32 v27, v34
	v_mov_b32_e32 v35, v36
	v_add_u32_e32 v54, s39, v193
	v_add_u32_e32 v5, s39, v194
	v_add_u32_e32 v55, 16, v54
	v_add_u32_e32 v56, 32, v54
	v_add_u32_e32 v57, 48, v54
	v_add_u32_e32 v58, 64, v54
	v_add_u32_e32 v59, 80, v54
	v_add_u32_e32 v60, 96, v54
	v_add_u32_e32 v61, 112, v54
	ds_read2st64_b32 v[6:7], v54 offset1:1
	ds_read2st64_b32 v[8:9], v55 offset0:2 offset1:3
	ds_read2st64_b32 v[10:11], v56 offset0:4 offset1:5
	ds_read2st64_b32 v[12:13], v57 offset0:6 offset1:7
	ds_read2st64_b32 v[14:15], v58 offset0:8 offset1:9
	ds_read2st64_b32 v[16:17], v59 offset0:10 offset1:11
	ds_read2st64_b32 v[18:19], v60 offset0:12 offset1:13
	ds_read2st64_b32 v[20:21], v61 offset0:14 offset1:15
	v_add_u32_e32 v54, 0x80, v54
	v_add_u32_e32 v55, 0x80, v55
	v_add_u32_e32 v56, 0x80, v56
	v_add_u32_e32 v57, 0x80, v57
	v_add_u32_e32 v58, 0x80, v58
	v_add_u32_e32 v59, 0x80, v59
	v_add_u32_e32 v60, 0x80, v60
	v_add_u32_e32 v61, 0x80, v61
	ds_read2st64_b32 v[38:39], v54 offset0:16 offset1:17
	ds_read2st64_b32 v[40:41], v55 offset0:18 offset1:19
	ds_read2st64_b32 v[42:43], v56 offset0:20 offset1:21
	ds_read2st64_b32 v[44:45], v57 offset0:22 offset1:23
	ds_read2st64_b32 v[46:47], v58 offset0:24 offset1:25
	ds_read2st64_b32 v[48:49], v59 offset0:26 offset1:27
	ds_read2st64_b32 v[50:51], v60 offset0:28 offset1:29
	ds_read2st64_b32 v[52:53], v61 offset0:30 offset1:31
	v_mov_b32_e32 v2, 0
	v_mov_b32_e32 v3, 0
	s_waitcnt lgkmcnt(8)
	v_pk_fma_f32 v[22:23], v[34:35], v[2:3], v[6:7] op_sel:[0,0,1] op_sel_hi:[0,1,0]
	v_pk_fma_f32 v[24:25], v[26:27], v[26:27], 0 op_sel:[1,0,0]
	v_pk_fma_f32 v[2:3], v[34:35], v[2:3], v[22:23] op_sel:[1,1,0] op_sel_hi:[1,0,1] neg_hi:[1,0,0]
	v_pk_fma_f32 v[26:27], v[26:27], v[26:27], v[24:25] op_sel:[0,1,0] op_sel_hi:[0,0,1] neg_hi:[1,0,0]
	v_pk_fma_f32 v[22:23], v[34:35], v[2:3], v[8:9] op_sel:[0,0,1] op_sel_hi:[0,1,0]
	v_pk_fma_f32 v[24:25], v[26:27], v[26:27], 0 op_sel:[1,0,0]
	v_pk_fma_f32 v[2:3], v[34:35], v[2:3], v[22:23] op_sel:[1,1,0] op_sel_hi:[1,0,1] neg_hi:[1,0,0]
	v_pk_fma_f32 v[26:27], v[26:27], v[26:27], v[24:25] op_sel:[0,1,0] op_sel_hi:[0,0,1] neg_hi:[1,0,0]
	v_pk_fma_f32 v[22:23], v[34:35], v[2:3], v[10:11] op_sel:[0,0,1] op_sel_hi:[0,1,0]
	v_pk_fma_f32 v[24:25], v[26:27], v[26:27], 0 op_sel:[1,0,0]
	v_pk_fma_f32 v[2:3], v[34:35], v[2:3], v[22:23] op_sel:[1,1,0] op_sel_hi:[1,0,1] neg_hi:[1,0,0]
	v_pk_fma_f32 v[26:27], v[26:27], v[26:27], v[24:25] op_sel:[0,1,0] op_sel_hi:[0,0,1] neg_hi:[1,0,0]
	v_pk_fma_f32 v[22:23], v[34:35], v[2:3], v[12:13] op_sel:[0,0,1] op_sel_hi:[0,1,0]
	v_pk_fma_f32 v[24:25], v[26:27], v[26:27], 0 op_sel:[1,0,0]
	v_pk_fma_f32 v[2:3], v[34:35], v[2:3], v[22:23] op_sel:[1,1,0] op_sel_hi:[1,0,1] neg_hi:[1,0,0]
	v_pk_fma_f32 v[26:27], v[26:27], v[26:27], v[24:25] op_sel:[0,1,0] op_sel_hi:[0,0,1] neg_hi:[1,0,0]
	v_pk_fma_f32 v[22:23], v[34:35], v[2:3], v[14:15] op_sel:[0,0,1] op_sel_hi:[0,1,0]
	s_nop 0
	v_pk_fma_f32 v[2:3], v[34:35], v[2:3], v[22:23] op_sel:[1,1,0] op_sel_hi:[1,0,1] neg_hi:[1,0,0]
	s_nop 0
	v_pk_fma_f32 v[22:23], v[34:35], v[2:3], v[16:17] op_sel:[0,0,1] op_sel_hi:[0,1,0]
	s_nop 0
	v_pk_fma_f32 v[2:3], v[34:35], v[2:3], v[22:23] op_sel:[1,1,0] op_sel_hi:[1,0,1] neg_hi:[1,0,0]
	s_nop 0
	v_pk_fma_f32 v[22:23], v[34:35], v[2:3], v[18:19] op_sel:[0,0,1] op_sel_hi:[0,1,0]
	s_nop 0
	v_pk_fma_f32 v[2:3], v[34:35], v[2:3], v[22:23] op_sel:[1,1,0] op_sel_hi:[1,0,1] neg_hi:[1,0,0]
	s_nop 0
	v_pk_fma_f32 v[22:23], v[34:35], v[2:3], v[20:21] op_sel:[0,0,1] op_sel_hi:[0,1,0]
	s_nop 0
	v_pk_fma_f32 v[2:3], v[34:35], v[2:3], v[22:23] op_sel:[1,1,0] op_sel_hi:[1,0,1] neg_hi:[1,0,0]
	s_nop 0
	s_waitcnt lgkmcnt(0)
	v_pk_fma_f32 v[22:23], v[34:35], v[2:3], v[38:39] op_sel:[0,0,1] op_sel_hi:[0,1,0]
	s_nop 0
	v_pk_fma_f32 v[2:3], v[34:35], v[2:3], v[22:23] op_sel:[1,1,0] op_sel_hi:[1,0,1] neg_hi:[1,0,0]
	s_nop 0
	v_pk_fma_f32 v[22:23], v[34:35], v[2:3], v[40:41] op_sel:[0,0,1] op_sel_hi:[0,1,0]
	s_nop 0
	v_pk_fma_f32 v[2:3], v[34:35], v[2:3], v[22:23] op_sel:[1,1,0] op_sel_hi:[1,0,1] neg_hi:[1,0,0]
	s_nop 0
	v_pk_fma_f32 v[22:23], v[34:35], v[2:3], v[42:43] op_sel:[0,0,1] op_sel_hi:[0,1,0]
	s_nop 0
	v_pk_fma_f32 v[2:3], v[34:35], v[2:3], v[22:23] op_sel:[1,1,0] op_sel_hi:[1,0,1] neg_hi:[1,0,0]
	s_nop 0
	v_pk_fma_f32 v[22:23], v[34:35], v[2:3], v[44:45] op_sel:[0,0,1] op_sel_hi:[0,1,0]
	s_nop 0
	v_pk_fma_f32 v[2:3], v[34:35], v[2:3], v[22:23] op_sel:[1,1,0] op_sel_hi:[1,0,1] neg_hi:[1,0,0]
	s_nop 0
	v_pk_fma_f32 v[22:23], v[34:35], v[2:3], v[46:47] op_sel:[0,0,1] op_sel_hi:[0,1,0]
	s_nop 0
	v_pk_fma_f32 v[2:3], v[34:35], v[2:3], v[22:23] op_sel:[1,1,0] op_sel_hi:[1,0,1] neg_hi:[1,0,0]
	s_nop 0
	v_pk_fma_f32 v[22:23], v[34:35], v[2:3], v[48:49] op_sel:[0,0,1] op_sel_hi:[0,1,0]
	s_nop 0
	v_pk_fma_f32 v[2:3], v[34:35], v[2:3], v[22:23] op_sel:[1,1,0] op_sel_hi:[1,0,1] neg_hi:[1,0,0]
	s_nop 0
	v_pk_fma_f32 v[22:23], v[34:35], v[2:3], v[50:51] op_sel:[0,0,1] op_sel_hi:[0,1,0]
	s_nop 0
	v_pk_fma_f32 v[2:3], v[34:35], v[2:3], v[22:23] op_sel:[1,1,0] op_sel_hi:[1,0,1] neg_hi:[1,0,0]
	s_nop 0
	v_pk_fma_f32 v[22:23], v[34:35], v[2:3], v[52:53] op_sel:[0,0,1] op_sel_hi:[0,1,0]
	s_nop 0
	v_pk_fma_f32 v[2:3], v[34:35], v[2:3], v[22:23] op_sel:[1,1,0] op_sel_hi:[1,0,1] neg_hi:[1,0,0]
	s_nop 0
	s_mov_b32 s39, 0x21000
	v_lshl_add_u32 v4, v210, 3, s39
	s_lshl_b32 s39, s38, 9
	v_add_u32_e32 v30, s39, v4
	ds_write_b64 v30, v[2:3]
	s_waitcnt lgkmcnt(0)
	s_barrier
	ds_read_b64 v[54:55], v4
	ds_read_b64 v[56:57], v4 offset:512
	ds_read_b64 v[58:59], v4 offset:1024
	ds_read_b64 v[60:61], v4 offset:1536
	ds_read_b64 v[62:63], v4 offset:2048
	ds_read_b64 v[64:65], v4 offset:2560
	ds_read_b64 v[36:37], v4 offset:3072
	ds_read_b64 v[28:29], v4 offset:3584
	v_mov_b32_e32 v30, 0
	v_mov_b32_e32 v31, 0
	s_cmp_eq_u32 s38, 0
	s_cbranch_scc0 .Ls5scan_c0
	v_mov_b32_e32 v32, v30
	v_mov_b32_e32 v33, v31
; #define LAS __attribute__((address_space(3)))
; __device__ __forceinline__ unsigned cvt_pk_bf16(float lo, float hi) { unsigned r; asm("v_cvt_pk_bf16_f32 %0, %1, %2" : "=v"(r) : "v"(lo), "v"(hi)); return r; }
; #define LDS_WAIT() asm volatile("s_waitcnt lgkmcnt(0)" ::: "memory")
; __device__ __forceinline__ void s5_prompt(const Args& a, LAS unsigned char* lds, int b, int g, int tid, int lane, int wave) {
;     ...
;     if (wave == 0) {
;         const LAS float* zp = (const LAS float*)ZS + lane;
;         LAS unsigned short* sp = (LAS unsigned short*)ZS + lane;
;         float sr = 0.f, si = 0.f;
; #pragma unroll 1
;         for (int jb = 0; jb < 16; ++jb) {
;             asm volatile("" : "+v"(zp), "+v"(sp));
;             float zr[8], zi[8];
; #pragma unroll
;             for (int i = 0; i < 8; ++i) { zr[i] = zp[i * (S5_PITCH / 4)]; zi[i] = zp[i * (S5_PITCH / 4) + 64]; }
;             LDS_WAIT();
; #pragma unroll
;             for (int i = 0; i < 8; ++i) {
;                 const unsigned w = cvt_pk_bf16(sr, si);
;                 sp[i * (S5_PITCH / 2)] = (unsigned short)(w & 0xffffu);
;                 sp[i * (S5_PITCH / 2) + 64] = (unsigned short)(w >> 16);
;                 const float nr = l16r * sr - l16i * si + zr[i], ni = l16r * si + l16i * sr + zi[i];
;                 sr = nr; si = ni;
;             }
;             zp += 8 * (S5_PITCH / 4); sp += 8 * (S5_PITCH / 2);
;         }
.Ls5scan_c0:
	s_waitcnt lgkmcnt(7)
	v_pk_fma_f32 v[22:23], v[26:27], v[30:31], v[54:55] op_sel:[1,0,0]
	s_nop 0
	v_pk_fma_f32 v[30:31], v[26:27], v[30:31], v[22:23] op_sel:[0,1,0] op_sel_hi:[0,0,1] neg_hi:[1,0,0]
	s_cmp_eq_u32 s38, 1
	s_cbranch_scc0 .Ls5scan_c1
	v_mov_b32_e32 v32, v30
	v_mov_b32_e32 v33, v31
.Ls5scan_c1:
	s_waitcnt lgkmcnt(6)
	v_pk_fma_f32 v[22:23], v[26:27], v[30:31], v[56:57] op_sel:[1,0,0]
	s_nop 0
	v_pk_fma_f32 v[30:31], v[26:27], v[30:31], v[22:23] op_sel:[0,1,0] op_sel_hi:[0,0,1] neg_hi:[1,0,0]
	s_cmp_eq_u32 s38, 2
	s_cbranch_scc0 .Ls5scan_c2
	v_mov_b32_e32 v32, v30
	v_mov_b32_e32 v33, v31
.Ls5scan_c2:
	s_waitcnt lgkmcnt(5)
	v_pk_fma_f32 v[22:23], v[26:27], v[30:31], v[58:59] op_sel:[1,0,0]
	s_nop 0
	v_pk_fma_f32 v[30:31], v[26:27], v[30:31], v[22:23] op_sel:[0,1,0] op_sel_hi:[0,0,1] neg_hi:[1,0,0]
	s_cmp_eq_u32 s38, 3
	s_cbranch_scc0 .Ls5scan_c3
	v_mov_b32_e32 v32, v30
	v_mov_b32_e32 v33, v31
.Ls5scan_c3:
	s_waitcnt lgkmcnt(4)
	v_pk_fma_f32 v[22:23], v[26:27], v[30:31], v[60:61] op_sel:[1,0,0]
	s_nop 0
	v_pk_fma_f32 v[30:31], v[26:27], v[30:31], v[22:23] op_sel:[0,1,0] op_sel_hi:[0,0,1] neg_hi:[1,0,0]
	s_cmp_eq_u32 s38, 4
	s_cbranch_scc0 .Ls5scan_c4
	v_mov_b32_e32 v32, v30
	v_mov_b32_e32 v33, v31
.Ls5scan_c4:
	s_waitcnt lgkmcnt(3)
	v_pk_fma_f32 v[22:23], v[26:27], v[30:31], v[62:63] op_sel:[1,0,0]
	s_nop 0
	v_pk_fma_f32 v[30:31], v[26:27], v[30:31], v[22:23] op_sel:[0,1,0] op_sel_hi:[0,0,1] neg_hi:[1,0,0]
	s_cmp_eq_u32 s38, 5
	s_cbranch_scc0 .Ls5scan_c5
	v_mov_b32_e32 v32, v30
	v_mov_b32_e32 v33, v31
.Ls5scan_c5:
	s_waitcnt lgkmcnt(2)
	v_pk_fma_f32 v[22:23], v[26:27], v[30:31], v[64:65] op_sel:[1,0,0]
	s_nop 0
	v_pk_fma_f32 v[30:31], v[26:27], v[30:31], v[22:23] op_sel:[0,1,0] op_sel_hi:[0,0,1] neg_hi:[1,0,0]
	s_cmp_eq_u32 s38, 6
	s_cbranch_scc0 .Ls5scan_c6
	v_mov_b32_e32 v32, v30
	v_mov_b32_e32 v33, v31
.Ls5scan_c6:
	s_waitcnt lgkmcnt(1)
	v_pk_fma_f32 v[22:23], v[26:27], v[30:31], v[36:37] op_sel:[1,0,0]
	s_nop 0
	v_pk_fma_f32 v[30:31], v[26:27], v[30:31], v[22:23] op_sel:[0,1,0] op_sel_hi:[0,0,1] neg_hi:[1,0,0]
	s_cmp_eq_u32 s38, 7
	s_cbranch_scc0 .Ls5scan_c7
	v_mov_b32_e32 v32, v30
	v_mov_b32_e32 v33, v31
; __device__ __forceinline__ unsigned cvt_pk_bf16(float lo, float hi) { unsigned r; asm("v_cvt_pk_bf16_f32 %0, %1, %2" : "=v"(r) : "v"(lo), "v"(hi)); return r; }
; #define LDS_WAIT() asm volatile("s_waitcnt lgkmcnt(0)" ::: "memory")
; __device__ __forceinline__ void s5_prompt(const Args& a, LAS unsigned char* lds, int b, int g, int tid, int lane, int wave) {
;     ...
;             for (int i = 0; i < 8; ++i) { zr[i] = zp[i * (S5_PITCH / 4)]; zi[i] = zp[i * (S5_PITCH / 4) + 64]; }
;             LDS_WAIT();
; #pragma unroll
;             for (int i = 0; i < 8; ++i) {
;                 const unsigned w = cvt_pk_bf16(sr, si);
;                 sp[i * (S5_PITCH / 2)] = (unsigned short)(w & 0xffffu);
;                 sp[i * (S5_PITCH / 2) + 64] = (unsigned short)(w >> 16);
;                 const float nr = l16r * sr - l16i * si + zr[i], ni = l16r * si + l16i * sr + zi[i];
;                 sr = nr; si = ni;
;             }
;             zp += 8 * (S5_PITCH / 4); sp += 8 * (S5_PITCH / 2);
;         }
;         a.out[O_PS5RE + (size_t)(b * NG + g) * NP + lane] = sr;
;         a.out[O_PS5IM + (size_t)(b * NG + g) * NP + lane] = si;
;     }
.Ls5scan_c7:
	s_waitcnt lgkmcnt(0)
	v_pk_fma_f32 v[22:23], v[26:27], v[30:31], v[28:29] op_sel:[1,0,0]
	s_nop 0
	v_pk_fma_f32 v[30:31], v[26:27], v[30:31], v[22:23] op_sel:[0,1,0] op_sel_hi:[0,0,1] neg_hi:[1,0,0]
	v_mov_b32_e32 v2, v32
	v_mov_b32_e32 v3, v33
	v_pk_fma_f32 v[22:23], v[34:35], v[2:3], v[6:7] op_sel:[0,0,1] op_sel_hi:[0,1,0]
	v_cvt_pk_bf16_f32 v24, v3, v2
	s_waitcnt lgkmcnt(13)
	v_pk_fma_f32 v[2:3], v[34:35], v[2:3], v[22:23] op_sel:[1,1,0] op_sel_hi:[1,0,1] neg_hi:[1,0,0]
	ds_write_b16 v5, v24
	ds_write_b16_d16_hi v5, v24 offset:128
	v_pk_fma_f32 v[22:23], v[34:35], v[2:3], v[8:9] op_sel:[0,0,1] op_sel_hi:[0,1,0]
	v_cvt_pk_bf16_f32 v25, v3, v2
	s_waitcnt lgkmcnt(13)
	v_pk_fma_f32 v[2:3], v[34:35], v[2:3], v[22:23] op_sel:[1,1,0] op_sel_hi:[1,0,1] neg_hi:[1,0,0]
	ds_write_b16 v5, v25 offset:528
	ds_write_b16_d16_hi v5, v25 offset:656
	v_pk_fma_f32 v[22:23], v[34:35], v[2:3], v[10:11] op_sel:[0,0,1] op_sel_hi:[0,1,0]
	v_cvt_pk_bf16_f32 v24, v3, v2
	s_waitcnt lgkmcnt(13)
	v_pk_fma_f32 v[2:3], v[34:35], v[2:3], v[22:23] op_sel:[1,1,0] op_sel_hi:[1,0,1] neg_hi:[1,0,0]
	ds_write_b16 v5, v24 offset:1056
	ds_write_b16_d16_hi v5, v24 offset:1184
	v_pk_fma_f32 v[22:23], v[34:35], v[2:3], v[12:13] op_sel:[0,0,1] op_sel_hi:[0,1,0]
	v_cvt_pk_bf16_f32 v25, v3, v2
	s_waitcnt lgkmcnt(13)
	v_pk_fma_f32 v[2:3], v[34:35], v[2:3], v[22:23] op_sel:[1,1,0] op_sel_hi:[1,0,1] neg_hi:[1,0,0]
	ds_write_b16 v5, v25 offset:1584
	ds_write_b16_d16_hi v5, v25 offset:1712
	v_pk_fma_f32 v[22:23], v[34:35], v[2:3], v[14:15] op_sel:[0,0,1] op_sel_hi:[0,1,0]
	v_cvt_pk_bf16_f32 v24, v3, v2
	s_waitcnt lgkmcnt(13)
	v_pk_fma_f32 v[2:3], v[34:35], v[2:3], v[22:23] op_sel:[1,1,0] op_sel_hi:[1,0,1] neg_hi:[1,0,0]
	ds_write_b16 v5, v24 offset:2112
	ds_write_b16_d16_hi v5, v24 offset:2240
	v_pk_fma_f32 v[22:23], v[34:35], v[2:3], v[16:17] op_sel:[0,0,1] op_sel_hi:[0,1,0]
	v_cvt_pk_bf16_f32 v25, v3, v2
	s_waitcnt lgkmcnt(13)
	v_pk_fma_f32 v[2:3], v[34:35], v[2:3], v[22:23] op_sel:[1,1,0] op_sel_hi:[1,0,1] neg_hi:[1,0,0]
	ds_write_b16 v5, v25 offset:2640
	ds_write_b16_d16_hi v5, v25 offset:2768
	v_pk_fma_f32 v[22:23], v[34:35], v[2:3], v[18:19] op_sel:[0,0,1] op_sel_hi:[0,1,0]
	v_cvt_pk_bf16_f32 v24, v3, v2
	s_waitcnt lgkmcnt(13)
	v_pk_fma_f32 v[2:3], v[34:35], v[2:3], v[22:23] op_sel:[1,1,0] op_sel_hi:[1,0,1] neg_hi:[1,0,0]
	ds_write_b16 v5, v24 offset:3168
	ds_write_b16_d16_hi v5, v24 offset:3296
	v_pk_fma_f32 v[22:23], v[34:35], v[2:3], v[20:21] op_sel:[0,0,1] op_sel_hi:[0,1,0]
	v_cvt_pk_bf16_f32 v25, v3, v2
	s_waitcnt lgkmcnt(13)
	v_pk_fma_f32 v[2:3], v[34:35], v[2:3], v[22:23] op_sel:[1,1,0] op_sel_hi:[1,0,1] neg_hi:[1,0,0]
	ds_write_b16 v5, v25 offset:3696
	ds_write_b16_d16_hi v5, v25 offset:3824
	v_pk_fma_f32 v[22:23], v[34:35], v[2:3], v[38:39] op_sel:[0,0,1] op_sel_hi:[0,1,0]
	v_cvt_pk_bf16_f32 v24, v3, v2
	s_waitcnt lgkmcnt(13)
	v_pk_fma_f32 v[2:3], v[34:35], v[2:3], v[22:23] op_sel:[1,1,0] op_sel_hi:[1,0,1] neg_hi:[1,0,0]
	ds_write_b16 v5, v24 offset:4224
	ds_write_b16_d16_hi v5, v24 offset:4352
	v_pk_fma_f32 v[22:23], v[34:35], v[2:3], v[40:41] op_sel:[0,0,1] op_sel_hi:[0,1,0]
	v_cvt_pk_bf16_f32 v25, v3, v2
	s_waitcnt lgkmcnt(13)
	v_pk_fma_f32 v[2:3], v[34:35], v[2:3], v[22:23] op_sel:[1,1,0] op_sel_hi:[1,0,1] neg_hi:[1,0,0]
	ds_write_b16 v5, v25 offset:4752
	ds_write_b16_d16_hi v5, v25 offset:4880
	v_pk_fma_f32 v[22:23], v[34:35], v[2:3], v[42:43] op_sel:[0,0,1] op_sel_hi:[0,1,0]
	v_cvt_pk_bf16_f32 v24, v3, v2
	s_waitcnt lgkmcnt(13)
	v_pk_fma_f32 v[2:3], v[34:35], v[2:3], v[22:23] op_sel:[1,1,0] op_sel_hi:[1,0,1] neg_hi:[1,0,0]
	ds_write_b16 v5, v24 offset:5280
	ds_write_b16_d16_hi v5, v24 offset:5408
	v_pk_fma_f32 v[22:23], v[34:35], v[2:3], v[44:45] op_sel:[0,0,1] op_sel_hi:[0,1,0]
	v_cvt_pk_bf16_f32 v25, v3, v2
	s_waitcnt lgkmcnt(13)
	v_pk_fma_f32 v[2:3], v[34:35], v[2:3], v[22:23] op_sel:[1,1,0] op_sel_hi:[1,0,1] neg_hi:[1,0,0]
	ds_write_b16 v5, v25 offset:5808
	ds_write_b16_d16_hi v5, v25 offset:5936
	v_pk_fma_f32 v[22:23], v[34:35], v[2:3], v[46:47] op_sel:[0,0,1] op_sel_hi:[0,1,0]
	v_cvt_pk_bf16_f32 v24, v3, v2
	s_waitcnt lgkmcnt(13)
	v_pk_fma_f32 v[2:3], v[34:35], v[2:3], v[22:23] op_sel:[1,1,0] op_sel_hi:[1,0,1] neg_hi:[1,0,0]
	ds_write_b16 v5, v24 offset:6336
	ds_write_b16_d16_hi v5, v24 offset:6464
	v_pk_fma_f32 v[22:23], v[34:35], v[2:3], v[48:49] op_sel:[0,0,1] op_sel_hi:[0,1,0]
	v_cvt_pk_bf16_f32 v25, v3, v2
	s_waitcnt lgkmcnt(13)
	v_pk_fma_f32 v[2:3], v[34:35], v[2:3], v[22:23] op_sel:[1,1,0] op_sel_hi:[1,0,1] neg_hi:[1,0,0]
	ds_write_b16 v5, v25 offset:6864
	ds_write_b16_d16_hi v5, v25 offset:6992
	v_pk_fma_f32 v[22:23], v[34:35], v[2:3], v[50:51] op_sel:[0,0,1] op_sel_hi:[0,1,0]
	v_cvt_pk_bf16_f32 v24, v3, v2
	s_waitcnt lgkmcnt(13)
	v_pk_fma_f32 v[2:3], v[34:35], v[2:3], v[22:23] op_sel:[1,1,0] op_sel_hi:[1,0,1] neg_hi:[1,0,0]
	ds_write_b16 v5, v24 offset:7392
	ds_write_b16_d16_hi v5, v24 offset:7520
	v_pk_fma_f32 v[22:23], v[34:35], v[2:3], v[52:53] op_sel:[0,0,1] op_sel_hi:[0,1,0]
	v_cvt_pk_bf16_f32 v25, v3, v2
	s_waitcnt lgkmcnt(13)
	v_pk_fma_f32 v[2:3], v[34:35], v[2:3], v[22:23] op_sel:[1,1,0] op_sel_hi:[1,0,1] neg_hi:[1,0,0]
	ds_write_b16 v5, v25 offset:7920
	ds_write_b16_d16_hi v5, v25 offset:8048
	v_mov_b32_e32 v2, v30
	v_mov_b32_e32 v3, v31
	s_andn2_b64 vcc, exec, s[18:19]
	s_cbranch_vccnz .LBB0_591
	s_and_b32 s38, s35, 0xffffffc0
	s_or_b32 s38, s36, s38
	s_ashr_i32 s39, s38, 31
	v_readlane_b32 s40, v254, 0
	s_lshl_b64 s[38:39], s[38:39], 8
	v_readlane_b32 s42, v254, 2
	v_readlane_b32 s43, v254, 3
	s_add_u32 s38, s42, s38
	s_addc_u32 s39, s43, s39
	v_lshlrev_b32_e32 v4, 2, v210
	v_mov_b32_e32 v5, v167
	v_lshl_add_u64 v[4:5], s[38:39], 0, v[4:5]
	v_add_co_u32_e32 v6, vcc, 0x4100000, v4
	v_readlane_b32 s41, v254, 1
	s_nop 0
	v_addc_co_u32_e32 v7, vcc, 0, v5, vcc
	v_add_co_u32_e32 v4, vcc, 0x4110000, v4
	global_store_dword v[6:7], v3, off
	s_nop 0
	v_addc_co_u32_e32 v5, vcc, 0, v5, vcc
	global_store_dword v[4:5], v2, off
